# S5 output pass: scan steps fused to four FMAs each; NA row-sum packed adds split
# speedup vs baseline: 1.0328x; 1.0057x over previous
.LBB0_587:
	s_or_b64 exec, exec, s[82:83]
	v_exp_f32_e32 v64, v64
	v_exp_f32_e32 v65, v65
	v_exp_f32_e32 v66, v66
	v_exp_f32_e32 v67, v67
	v_exp_f32_e32 v68, v68
	v_exp_f32_e32 v69, v69
	v_exp_f32_e32 v70, v70
	v_exp_f32_e32 v71, v71
	v_exp_f32_e32 v80, v48
	v_exp_f32_e32 v81, v49
	v_exp_f32_e32 v82, v50
	v_exp_f32_e32 v83, v51
	v_cvt_pk_bf16_f32 v48, v64, v65
	v_cvt_pk_bf16_f32 v49, v66, v67
	v_cvt_pk_bf16_f32 v50, v68, v69
	v_cvt_pk_bf16_f32 v51, v70, v71
	v_exp_f32_e32 v72, v72
	v_exp_f32_e32 v73, v73
	s_waitcnt lgkmcnt(0)
	v_mfma_f32_32x32x16_bf16 v[16:31], v[166:169], v[48:51], v[16:31]
	v_exp_f32_e32 v74, v74
	v_exp_f32_e32 v75, v75
	v_exp_f32_e32 v76, v76
	v_exp_f32_e32 v77, v77
	v_exp_f32_e32 v78, v78
	v_exp_f32_e32 v79, v79
	v_exp_f32_e32 v52, v52
	v_mfma_f32_32x32x16_bf16 v[0:15], v[162:165], v[48:51], v[0:15]
	v_cvt_pk_bf16_f32 v48, v72, v73
	v_cvt_pk_bf16_f32 v49, v74, v75
	v_cvt_pk_bf16_f32 v50, v76, v77
	v_cvt_pk_bf16_f32 v51, v78, v79
	v_exp_f32_e32 v53, v53
	v_exp_f32_e32 v54, v54
	v_exp_f32_e32 v55, v55
	v_mfma_f32_32x32x16_bf16 v[16:31], v[158:161], v[48:51], v[16:31]
	v_add_f32_e64 v64, v64, 0
	v_add_f32_e64 v65, v65, 0
	v_exp_f32_e32 v56, v56
	v_add_f32_e64 v64, v80, v64
	v_add_f32_e64 v65, v81, v65
	v_exp_f32_e32 v57, v57
	v_add_f32_e64 v64, v66, v64
	v_add_f32_e64 v65, v67, v65
	v_exp_f32_e32 v58, v58
	v_add_f32_e64 v64, v82, v64
	v_add_f32_e64 v65, v83, v65
	v_mfma_f32_32x32x16_bf16 v[0:15], v[154:157], v[48:51], v[0:15]
	v_cvt_pk_bf16_f32 v48, v80, v81
	v_cvt_pk_bf16_f32 v49, v82, v83
	v_cvt_pk_bf16_f32 v50, v52, v53
	v_cvt_pk_bf16_f32 v51, v54, v55
	v_add_f32_e64 v64, v68, v64
	v_add_f32_e64 v65, v69, v65
	v_exp_f32_e32 v59, v59
	v_exp_f32_e32 v60, v60
	v_mfma_f32_32x32x16_bf16 v[16:31], v[150:153], v[48:51], v[16:31]
	v_exp_f32_e32 v61, v61
	v_exp_f32_e32 v62, v62
	v_exp_f32_e32 v63, v63
	v_add_f32_e64 v52, v52, v64
	v_add_f32_e64 v53, v53, v65
	s_andn2_b64 s[88:89], s[88:89], exec
	v_add_f32_e64 v52, v70, v52
	v_add_f32_e64 v53, v71, v53
	v_mfma_f32_32x32x16_bf16 v[0:15], v[146:149], v[48:51], v[0:15]
	v_add_f32_e64 v48, v54, v52
	v_add_f32_e64 v49, v55, v53
	v_cvt_pk_bf16_f32 v50, v60, v61
	v_add_f32_e64 v48, v72, v48
	v_add_f32_e64 v49, v73, v49
	v_cvt_pk_bf16_f32 v51, v62, v63
	v_add_f32_e64 v52, v56, v48
	v_add_f32_e64 v53, v57, v49
	v_cvt_pk_bf16_f32 v48, v56, v57
	v_cvt_pk_bf16_f32 v49, v58, v59
	v_add_f32_e64 v52, v74, v52
	v_add_f32_e64 v53, v75, v53
	v_mfma_f32_32x32x16_bf16 v[16:31], v[142:145], v[48:51], v[16:31]
	v_add_f32_e64 v52, v58, v52
	v_add_f32_e64 v53, v59, v53
	v_add_f32_e64 v52, v76, v52
	v_add_f32_e64 v53, v77, v53
	v_add_f32_e64 v52, v60, v52
	v_add_f32_e64 v53, v61, v53
	v_add_f32_e64 v52, v78, v52
	v_add_f32_e64 v53, v79, v53
	v_mfma_f32_32x32x16_bf16 v[0:15], v[138:141], v[48:51], v[0:15]
	v_add_f32_e64 v52, v62, v52
	v_add_f32_e64 v53, v63, v53
	v_add_f32_e32 v52, v52, v53
	v_add_f32_e32 v208, v208, v52

.LBB0_644:
	v_cndmask_b32_e64 v127, v55, v51, s[8:9]
	v_cndmask_b32_e64 v126, v54, v50, s[8:9]
	v_cndmask_b32_e64 v125, v53, v49, s[8:9]
	v_cndmask_b32_e64 v124, v52, v48, s[8:9]
	s_mov_b64 s[14:15], -1
	s_andn2_b64 vcc, exec, s[10:11]
	v_mfma_f32_32x32x16_bf16 v[32:47], v[124:127], v[56:59], 0
	s_nop 11
	v_cvt_pk_bf16_f32 v32, v32, v33
	v_cvt_pk_bf16_f32 v33, v34, v35
	v_cvt_pk_bf16_f32 v34, v36, v37
	v_cvt_pk_bf16_f32 v35, v38, v39
	v_cvt_pk_bf16_f32 v36, v40, v41
	v_cvt_pk_bf16_f32 v37, v42, v43
	v_cvt_pk_bf16_f32 v38, v44, v45
	v_cvt_pk_bf16_f32 v39, v46, v47
	ds_write2_b64 v205, v[32:33], v[34:35] offset1:2
	ds_write2_b64 v205, v[36:37], v[38:39] offset0:4 offset1:6
	v_mfma_f32_32x32x16_bf16 v[32:47], v[124:127], v[60:63], 0
	s_nop 11
	v_cvt_pk_bf16_f32 v32, v32, v33
	v_cvt_pk_bf16_f32 v33, v34, v35
	v_cvt_pk_bf16_f32 v34, v36, v37
	v_cvt_pk_bf16_f32 v35, v38, v39
	v_add_u32_e32 v36, 0x800, v205
	ds_write2_b64 v36, v[32:33], v[34:35] offset0:64 offset1:66
	v_cvt_pk_bf16_f32 v32, v40, v41
	v_cvt_pk_bf16_f32 v33, v42, v43
	v_cvt_pk_bf16_f32 v34, v44, v45
	v_cvt_pk_bf16_f32 v35, v46, v47
	ds_write2_b64 v36, v[32:33], v[34:35] offset0:68 offset1:70
	v_mfma_f32_32x32x16_bf16 v[32:47], v[124:127], v[64:67], 0
	s_nop 11
	v_cvt_pk_bf16_f32 v32, v32, v33
	v_cvt_pk_bf16_f32 v33, v34, v35
	v_cvt_pk_bf16_f32 v34, v36, v37
	v_cvt_pk_bf16_f32 v35, v38, v39
	v_add_u32_e32 v36, 0x1000, v205
	ds_write2_b64 v36, v[32:33], v[34:35] offset0:128 offset1:130
	v_cvt_pk_bf16_f32 v32, v40, v41
	v_cvt_pk_bf16_f32 v33, v42, v43
	v_cvt_pk_bf16_f32 v34, v44, v45
	v_cvt_pk_bf16_f32 v35, v46, v47
	ds_write2_b64 v36, v[32:33], v[34:35] offset0:132 offset1:134
	v_mfma_f32_32x32x16_bf16 v[32:47], v[124:127], v[68:71], 0
	s_nop 11
	v_cvt_pk_bf16_f32 v32, v32, v33
	v_cvt_pk_bf16_f32 v33, v34, v35
	v_cvt_pk_bf16_f32 v34, v36, v37
	v_cvt_pk_bf16_f32 v35, v38, v39
	v_add_u32_e32 v36, 0x1800, v205
	ds_write2_b64 v36, v[32:33], v[34:35] offset0:192 offset1:194
	v_cvt_pk_bf16_f32 v32, v40, v41
	v_cvt_pk_bf16_f32 v33, v42, v43
	v_cvt_pk_bf16_f32 v34, v44, v45
	v_cvt_pk_bf16_f32 v35, v46, v47
	ds_write2_b64 v36, v[32:33], v[34:35] offset0:196 offset1:198
	s_waitcnt lgkmcnt(0)
	v_add_u32_e32 v40, s20, v199
	ds_read_b128 v[32:35], v40
	ds_read_b128 v[36:39], v40 offset:5120
	ds_read_b128 v[138:141], v40 offset:16
	ds_read_b128 v[142:145], v40 offset:5136
	s_waitcnt lgkmcnt(3)
	v_lshlrev_b32_e32 v163, 16, v32
	v_and_b32_e32 v157, 0xffff0000, v32
	v_lshlrev_b32_e32 v151, 16, v33
	v_and_b32_e32 v137, 0xffff0000, v33
	v_mul_f32_e64 v32, v118, v122
	v_mul_f32_e64 v33, v119, v122
	s_waitcnt lgkmcnt(2)
	v_lshlrev_b32_e32 v162, 16, v36
	v_fma_f32 v182, v120, v112, -v32
	v_fma_f32 v183, v121, v112, -v33
	v_fma_f32 v178, v120, v112, v32
	v_cndmask_b32_e64 v32, 0, 1, s[10:11]
	v_and_b32_e32 v156, 0xffff0000, v36
	v_lshlrev_b32_e32 v150, 16, v37
	v_and_b32_e32 v136, 0xffff0000, v37
	v_lshlrev_b32_e32 v133, 16, v34
	v_lshlrev_b32_e32 v132, 16, v38
	v_and_b32_e32 v131, 0xffff0000, v34
	v_and_b32_e32 v130, 0xffff0000, v38
	v_lshlrev_b32_e32 v129, 16, v35
	v_lshlrev_b32_e32 v128, 16, v39
	v_and_b32_e32 v127, 0xffff0000, v35
	v_and_b32_e32 v126, 0xffff0000, v39
	s_waitcnt lgkmcnt(1)
	v_lshlrev_b32_e32 v125, 16, v138
	s_waitcnt lgkmcnt(0)
	v_lshlrev_b32_e32 v124, 16, v142
	v_and_b32_e32 v47, 0xffff0000, v138
	v_and_b32_e32 v46, 0xffff0000, v142
	v_lshlrev_b32_e32 v45, 16, v139
	v_lshlrev_b32_e32 v44, 16, v143
	v_and_b32_e32 v43, 0xffff0000, v139
	v_and_b32_e32 v42, 0xffff0000, v143
	v_lshlrev_b32_e32 v41, 16, v140
	v_lshlrev_b32_e32 v40, 16, v144
	v_and_b32_e32 v39, 0xffff0000, v140
	v_and_b32_e32 v38, 0xffff0000, v144
	v_lshlrev_b32_e32 v37, 16, v141
	v_lshlrev_b32_e32 v36, 16, v145
	v_and_b32_e32 v35, 0xffff0000, v145
	v_and_b32_e32 v34, 0xffff0000, v141
	v_cmp_ne_u32_e64 s[4:5], 1, v32
	v_mov_b32_e32 v179, v183
	s_cbranch_vccnz .LBB0_646
	v_add_f32_e64 v168, v178, v35
	v_add_f32_e64 v169, v179, v34
	v_add_f32_e64 v176, v183, v34
	v_add_f32_e64 v177, v182, v35
	v_fma_f32 v32, v118, v168, v36
	v_fma_f32 v33, -v119, v168, v37
	s_mov_b64 s[14:15], 0
	v_fma_f32 v138, v120, v176, v32
	v_fma_f32 v139, v121, v176, v33
	v_fma_f32 v32, v118, v139, v39
	v_fma_f32 v141, -v119, v138, v32
	v_fma_f32 v32, v119, v139, v38
	v_fma_f32 v140, v118, v138, v32
	v_fma_f32 v32, v118, v140, v40
	v_fma_f32 v33, -v119, v140, v41
	v_fma_f32 v144, v120, v141, v32
	v_fma_f32 v145, v121, v141, v33
	v_fma_f32 v32, v118, v145, v43
	v_fma_f32 v135, -v119, v144, v32
	v_fma_f32 v32, v119, v145, v42
	v_fma_f32 v134, v118, v144, v32
	v_fma_f32 v32, v118, v134, v44
	v_fma_f32 v33, -v119, v134, v45
	v_fma_f32 v146, v120, v135, v32
	v_fma_f32 v147, v121, v135, v33
	v_mul_f32_e32 v32, v118, v147
	v_fma_f32 v33, -v119, v146, v32
	v_mul_f32_e32 v32, v119, v147
	v_fma_f32 v122, v118, v146, v32
	v_mov_b32_e32 v123, v33
	v_add_f32_e64 v122, v122, v46
	v_add_f32_e64 v123, v123, v47
	v_fma_f32 v32, v118, v122, v124
	v_fma_f32 v33, -v119, v122, v125
	v_fma_f32 v148, v120, v123, v32
	v_fma_f32 v149, v121, v123, v33
	v_fma_f32 v32, v118, v149, v127
	v_fma_f32 v153, -v119, v148, v32
	v_fma_f32 v32, v119, v149, v126
	v_fma_f32 v152, v118, v148, v32
	v_fma_f32 v32, v118, v153, v129
	v_fma_f32 v159, -v119, v152, v32
	v_fma_f32 v32, v119, v153, v128
	v_fma_f32 v158, v118, v152, v32
	v_mul_f32_e32 v32, v118, v159
	v_fma_f32 v33, -v119, v158, v32
	v_mul_f32_e32 v32, v119, v159
	v_fma_f32 v142, v118, v158, v32
	v_mov_b32_e32 v143, v33
	v_add_f32_e64 v142, v142, v130
	v_add_f32_e64 v143, v143, v131
	v_fma_f32 v32, v118, v143, v133
	v_fma_f32 v165, -v119, v142, v32
	v_fma_f32 v32, v119, v143, v132
	v_fma_f32 v164, v118, v142, v32
	v_mul_f32_e32 v32, v118, v165
	v_fma_f32 v33, -v119, v164, v32
	v_mul_f32_e32 v32, v119, v165
	v_fma_f32 v154, v118, v164, v32
	v_mov_b32_e32 v155, v33
	v_add_f32_e64 v154, v154, v136
	v_add_f32_e64 v155, v155, v137
	v_fma_f32 v32, v118, v155, v151
	v_fma_f32 v167, -v119, v154, v32
	v_fma_f32 v32, v119, v155, v150
	v_fma_f32 v166, v118, v154, v32
	v_mul_f32_e32 v32, v118, v167
	v_fma_f32 v33, -v119, v166, v32
	v_mul_f32_e32 v32, v119, v167
	v_fma_f32 v160, v118, v166, v32
	v_mov_b32_e32 v161, v33
	v_add_f32_e64 v160, v160, v156
	v_add_f32_e64 v161, v161, v157
	v_fma_f32 v32, v118, v161, v163
	v_fma_f32 v33, -v119, v160, v32
	v_fma_f32 v32, v119, v161, v162
	v_fma_f32 v32, v118, v160, v32
	v_mov_b32_e32 v112, v32
	v_mov_b32_e32 v180, v33
.LBB0_646:
	s_andn2_b64 vcc, exec, s[14:15]
	s_cbranch_vccnz .LBB0_648
	v_add_f32_e64 v32, v178, v162
	v_add_f32_e64 v33, v179, v163
	v_fma_f32 v112, v118, v33, v157
	v_fma_f32 v161, -v119, v32, v112
	v_fma_f32 v112, v119, v33, v156
	v_fma_f32 v160, v118, v32, v112
	v_fma_f32 v122, v118, v160, v150
	v_fma_f32 v123, -v119, v160, v151
	v_fma_f32 v166, v120, v161, v122
	v_fma_f32 v167, v121, v161, v123
	v_fma_f32 v112, v118, v167, v137
	v_fma_f32 v155, -v119, v166, v112
	v_fma_f32 v112, v119, v167, v136
	v_fma_f32 v154, v118, v166, v112
	v_fma_f32 v122, v118, v154, v132
	v_fma_f32 v123, -v119, v154, v133
	v_fma_f32 v164, v120, v155, v122
	v_fma_f32 v165, v121, v155, v123
	v_fma_f32 v112, v118, v165, v131
	v_fma_f32 v143, -v119, v164, v112
	v_fma_f32 v112, v119, v165, v130
	v_fma_f32 v142, v118, v164, v112
	v_fma_f32 v122, v118, v142, v128
	v_fma_f32 v123, -v119, v142, v129
	v_fma_f32 v158, v120, v143, v122
	v_fma_f32 v159, v121, v143, v123
	v_fma_f32 v112, v118, v159, v127
	v_fma_f32 v153, -v119, v158, v112
	v_fma_f32 v112, v119, v159, v126
	v_fma_f32 v152, v118, v158, v112
	v_fma_f32 v112, v118, v153, v125
	v_fma_f32 v149, -v119, v152, v112
	v_fma_f32 v112, v119, v153, v124
	v_fma_f32 v148, v118, v152, v112
	v_fma_f32 v112, v118, v149, v47
	v_fma_f32 v123, -v119, v148, v112
	v_fma_f32 v112, v119, v149, v46
	v_fma_f32 v122, v118, v148, v112
	v_mov_b32_e32 v112, v32
	v_fma_f32 v46, v118, v123, v45
	v_fma_f32 v147, -v119, v122, v46
	v_fma_f32 v46, v119, v123, v44
	v_fma_f32 v146, v118, v122, v46
	v_fma_f32 v44, v118, v147, v43
	v_fma_f32 v135, -v119, v146, v44
	v_fma_f32 v44, v119, v147, v42
	v_fma_f32 v134, v118, v146, v44
	v_fma_f32 v42, v118, v135, v41
	v_fma_f32 v145, -v119, v134, v42
	v_fma_f32 v42, v119, v135, v40
	v_fma_f32 v144, v118, v134, v42
	v_fma_f32 v40, v118, v145, v39
	v_fma_f32 v141, -v119, v144, v40
	v_fma_f32 v40, v119, v145, v38
	v_fma_f32 v140, v118, v144, v40
	v_fma_f32 v38, v118, v141, v37
	v_fma_f32 v139, -v119, v140, v38
	v_fma_f32 v38, v119, v141, v36
	v_fma_f32 v138, v118, v140, v38
	v_fma_f32 v36, -v120, v138, v34
	v_fma_f32 v37, v121, v138, v35
	v_fma_f32 v180, v118, v139, v36
	v_fma_f32 v36, v118, v139, v36
	v_fma_f32 v181, v119, v139, v37
	v_mov_b32_e32 v168, v181
	v_mov_b32_e32 v176, v180
	v_mov_b32_e32 v32, v181
.LBB0_648:
	v_add_u32_e32 v34, s21, v200
	v_cvt_pk_bf16_f32 v33, v33, v112
	v_cvt_pk_bf16_f32 v35, v161, v160
	v_add_u32_e32 v36, 0x2800, v34
	ds_write2_b32 v36, v33, v35 offset1:68
	v_cvt_pk_bf16_f32 v33, v167, v166
	v_cvt_pk_bf16_f32 v35, v155, v154
	ds_write2_b32 v36, v33, v35 offset0:136 offset1:204
	v_cvt_pk_bf16_f32 v33, v165, v164
	v_cvt_pk_bf16_f32 v35, v143, v142
	v_add_u32_e32 v36, 0x2c00, v34
	ds_write2_b32 v36, v33, v35 offset0:16 offset1:84
	v_cvt_pk_bf16_f32 v33, v159, v158
	v_cvt_pk_bf16_f32 v35, v153, v152
	ds_write2_b32 v36, v33, v35 offset0:152 offset1:220
	v_cvt_pk_bf16_f32 v33, v149, v148
	v_cvt_pk_bf16_f32 v35, v123, v122
	v_add_u32_e32 v36, 0x3000, v34
	ds_write2_b32 v36, v33, v35 offset0:32 offset1:100
	v_cvt_pk_bf16_f32 v33, v147, v146
	v_cvt_pk_bf16_f32 v35, v135, v134
	ds_write2_b32 v36, v33, v35 offset0:168 offset1:236
	v_cvt_pk_bf16_f32 v33, v145, v144
	v_cvt_pk_bf16_f32 v35, v141, v140
	v_add_u32_e32 v34, 0x3400, v34
	ds_write2_b32 v34, v33, v35 offset0:48 offset1:116
	v_cvt_pk_bf16_f32 v33, v139, v138
	v_cvt_pk_bf16_f32 v35, v176, v168
	ds_write2_b32 v34, v33, v35 offset0:184 offset1:252
	v_add_u32_e32 v33, s22, v199
	ds_read_b128 v[34:37], v33
	ds_read_b128 v[38:41], v33 offset:5120
	ds_read_b128 v[136:139], v33 offset:16
	ds_read_b128 v[144:147], v33 offset:5136
	v_mul_f32_e64 v33, v119, v32
	v_mul_f32_e64 v32, v118, v32
	s_waitcnt lgkmcnt(3)
	v_lshlrev_b32_e32 v167, 16, v34
	v_fma_f32 v122, v120, v180, -v32
	v_fma_f32 v123, v121, v180, -v33
	v_fma_f32 v178, v120, v180, v32
	s_waitcnt lgkmcnt(2)
	v_lshlrev_b32_e32 v166, 16, v38
	v_and_b32_e32 v161, 0xffff0000, v34
	v_and_b32_e32 v160, 0xffff0000, v38
	v_lshlrev_b32_e32 v159, 16, v35
	v_lshlrev_b32_e32 v158, 16, v39
	v_and_b32_e32 v143, 0xffff0000, v35
	v_and_b32_e32 v142, 0xffff0000, v39
	v_lshlrev_b32_e32 v135, 16, v36
	v_lshlrev_b32_e32 v134, 16, v40
	v_and_b32_e32 v131, 0xffff0000, v36
	v_and_b32_e32 v130, 0xffff0000, v40
	v_lshlrev_b32_e32 v129, 16, v37
	v_lshlrev_b32_e32 v128, 16, v41
	v_and_b32_e32 v127, 0xffff0000, v37
	v_and_b32_e32 v126, 0xffff0000, v41
	s_waitcnt lgkmcnt(1)
	v_lshlrev_b32_e32 v125, 16, v136
	s_waitcnt lgkmcnt(0)
	v_lshlrev_b32_e32 v124, 16, v144
	v_and_b32_e32 v47, 0xffff0000, v136
	v_and_b32_e32 v46, 0xffff0000, v144
	v_lshlrev_b32_e32 v45, 16, v137
	v_lshlrev_b32_e32 v44, 16, v145
	v_and_b32_e32 v43, 0xffff0000, v137
	v_and_b32_e32 v42, 0xffff0000, v145
	v_lshlrev_b32_e32 v41, 16, v138
	v_lshlrev_b32_e32 v40, 16, v146
	v_and_b32_e32 v39, 0xffff0000, v138
	v_and_b32_e32 v38, 0xffff0000, v146
	v_lshlrev_b32_e32 v37, 16, v139
	v_lshlrev_b32_e32 v36, 16, v147
	v_and_b32_e32 v35, 0xffff0000, v139
	v_and_b32_e32 v34, 0xffff0000, v147
	v_mov_b32_e32 v179, v123
	s_and_b64 vcc, exec, s[4:5]
	s_mov_b64 s[4:5], -1
	s_cbranch_vccnz .LBB0_650
	v_add_f32_e64 v150, v178, v34
	v_add_f32_e64 v151, v179, v35
	s_mov_b64 s[4:5], 0
	v_fma_f32 v32, v118, v150, v36
	v_fma_f32 v33, -v119, v150, v37
	v_fma_f32 v136, v120, v151, v32
	v_fma_f32 v137, v121, v151, v33
	v_fma_f32 v32, v118, v137, v39
	v_fma_f32 v139, -v119, v136, v32
	v_fma_f32 v32, v119, v137, v38
	v_fma_f32 v138, v118, v136, v32
	v_fma_f32 v32, v118, v138, v40
	v_fma_f32 v33, -v119, v138, v41
	v_fma_f32 v144, v120, v139, v32
	v_fma_f32 v145, v121, v139, v33
	v_fma_f32 v32, v118, v145, v43
	v_fma_f32 v133, -v119, v144, v32
	v_fma_f32 v32, v119, v145, v42
	v_fma_f32 v132, v118, v144, v32
	v_fma_f32 v32, v118, v132, v44
	v_fma_f32 v33, -v119, v132, v45
	v_fma_f32 v146, v120, v133, v32
	v_fma_f32 v147, v121, v133, v33
	v_fma_f32 v32, v118, v147, v47
	v_fma_f32 v33, -v119, v146, v32
	v_fma_f32 v32, v119, v147, v46
	v_fma_f32 v32, v118, v146, v32
	v_fma_f32 v122, v118, v32, v124
	v_fma_f32 v123, -v119, v32, v125
	v_fma_f32 v148, v120, v33, v122
	v_fma_f32 v149, v121, v33, v123
	v_fma_f32 v112, v118, v149, v127
	v_fma_f32 v153, -v119, v148, v112
	v_fma_f32 v112, v119, v149, v126
	v_fma_f32 v152, v118, v148, v112
	v_fma_f32 v112, v118, v153, v129
	v_fma_f32 v157, -v119, v152, v112
	v_fma_f32 v112, v119, v153, v128
	v_fma_f32 v156, v118, v152, v112
	v_mul_f32_e32 v112, v118, v157
	v_fma_f32 v123, -v119, v156, v112
	v_mul_f32_e32 v112, v119, v157
	v_fma_f32 v140, v118, v156, v112
	v_mov_b32_e32 v141, v123
	v_add_f32_e64 v140, v140, v130
	v_add_f32_e64 v141, v141, v131
	v_fma_f32 v112, v118, v141, v135
	v_fma_f32 v169, -v119, v140, v112
	v_fma_f32 v112, v119, v141, v134
	v_fma_f32 v168, v118, v140, v112
	v_mul_f32_e32 v112, v118, v169
	v_fma_f32 v123, -v119, v168, v112
	v_mul_f32_e32 v112, v119, v169
	v_fma_f32 v154, v118, v168, v112
	v_mov_b32_e32 v155, v123
	v_add_f32_e64 v154, v154, v142
	v_add_f32_e64 v155, v155, v143
	v_fma_f32 v112, v118, v155, v159
	v_fma_f32 v177, -v119, v154, v112
	v_fma_f32 v112, v119, v155, v158
	v_fma_f32 v176, v118, v154, v112
	v_mul_f32_e32 v112, v118, v177
	v_fma_f32 v123, -v119, v176, v112
	v_mul_f32_e32 v112, v119, v177
	v_fma_f32 v162, v118, v176, v112
	v_mov_b32_e32 v163, v123
	v_add_f32_e64 v162, v162, v160
	v_add_f32_e64 v163, v163, v161
	v_mul_f32_e32 v112, v118, v163
	v_fma_f32 v123, -v119, v162, v112
	v_mul_f32_e32 v112, v119, v163
	v_fma_f32 v164, v118, v162, v112
	v_mov_b32_e32 v165, v123
	v_add_f32_e64 v164, v164, v166
	v_add_f32_e64 v165, v165, v167
	v_mov_b32_e32 v112, v165
	v_mov_b32_e32 v122, v164
.LBB0_650:
	s_andn2_b64 vcc, exec, s[4:5]
	s_cbranch_vccnz .LBB0_643
	v_add_f32_e64 v164, v178, v166
	v_add_f32_e64 v165, v179, v167
	v_fma_f32 v32, v118, v165, v161
	v_fma_f32 v163, -v119, v164, v32
	v_fma_f32 v32, v119, v165, v160
	v_fma_f32 v162, v118, v164, v32
	v_fma_f32 v32, v118, v162, v158
	v_fma_f32 v33, -v119, v162, v159
	v_fma_f32 v176, v120, v163, v32
	v_fma_f32 v177, v121, v163, v33
	v_fma_f32 v32, v118, v177, v143
	v_fma_f32 v155, -v119, v176, v32
	v_fma_f32 v32, v119, v177, v142
	v_fma_f32 v154, v118, v176, v32
	v_fma_f32 v32, v118, v154, v134
	v_fma_f32 v33, -v119, v154, v135
	v_fma_f32 v168, v120, v155, v32
	v_fma_f32 v169, v121, v155, v33
	v_fma_f32 v32, v118, v169, v131
	v_fma_f32 v141, -v119, v168, v32
	v_fma_f32 v32, v119, v169, v130
	v_fma_f32 v140, v118, v168, v32
	v_fma_f32 v32, v118, v140, v128
	v_fma_f32 v33, -v119, v140, v129
	v_fma_f32 v156, v120, v141, v32
	v_fma_f32 v157, v121, v141, v33
	v_fma_f32 v32, v118, v157, v127
	v_fma_f32 v153, -v119, v156, v32
	v_fma_f32 v32, v119, v157, v126
	v_fma_f32 v152, v118, v156, v32
	v_fma_f32 v32, v118, v153, v125
	v_fma_f32 v149, -v119, v152, v32
	v_fma_f32 v32, v119, v153, v124
	v_fma_f32 v148, v118, v152, v32
	v_fma_f32 v32, v118, v149, v47
	v_fma_f32 v33, -v119, v148, v32
	v_fma_f32 v32, v119, v149, v46
	v_fma_f32 v32, v118, v148, v32
	v_fma_f32 v46, v118, v33, v45
	v_fma_f32 v147, -v119, v32, v46
	v_fma_f32 v46, v119, v33, v44
	v_fma_f32 v146, v118, v32, v46
	v_fma_f32 v44, v118, v147, v43
	v_fma_f32 v133, -v119, v146, v44
	v_fma_f32 v44, v119, v147, v42
	v_fma_f32 v132, v118, v146, v44
	v_fma_f32 v42, v118, v133, v41
	v_fma_f32 v145, -v119, v132, v42
	v_fma_f32 v42, v119, v133, v40
	v_fma_f32 v144, v118, v132, v42
	v_fma_f32 v40, v118, v145, v39
	v_fma_f32 v139, -v119, v144, v40
	v_fma_f32 v40, v119, v145, v38
	v_fma_f32 v138, v118, v144, v40
	v_fma_f32 v38, v118, v139, v37
	v_fma_f32 v137, -v119, v138, v38
	v_fma_f32 v38, v119, v139, v36
	v_fma_f32 v136, v118, v138, v38
	v_mul_f32_e64 v36, v118, v136
	v_fma_f32 v37, -v119, v136, v35
	v_fma_f32 v38, v120, v136, -v36
	v_fma_f32 v123, v121, v137, v37
	v_fma_f32 v36, v120, v137, v36
	v_add_f32_e64 v122, v36, v34
	v_mov_b32_e32 v150, v122
	v_mov_b32_e32 v112, v123
	v_mov_b32_e32 v151, v123
	s_branch .LBB0_643
